# p0_ada silu(cond) staging: 24 loads in flight + one wait instead of 24 serialized load/wait rounds (on top of LDS-DMA LN staging + astat MFMA order + unscaled MFMA + handoff edits)
# baseline (speedup 1.0000x reference)
.LBB0_11:
	s_or_b64 exec, exec, s[2:3]
	s_load_dwordx16 s[36:51], s[0:1], 0x0
	s_load_dwordx16 s[12:27], s[0:1], 0x40
	s_lshr_b32 s1, s6, 6
	s_add_u32 s92, s64, 0x100000
	s_addc_u32 s93, s65, 0
	s_add_u32 s0, s64, 0x22600000
	v_writelane_b32 v254, s0, 5
	s_addc_u32 s0, s65, 0
	v_writelane_b32 v254, s0, 6
	s_add_u32 s0, s64, 0x22c00000
	v_writelane_b32 v254, s0, 7
	s_addc_u32 s0, s65, 0
	v_writelane_b32 v254, s0, 8
	s_add_u32 s0, s64, 0x23000000
	v_writelane_b32 v254, s0, 9
	s_addc_u32 s0, s65, 0
	v_writelane_b32 v254, s0, 10
	s_add_u32 s0, s64, 0x23200000
	v_writelane_b32 v254, s0, 11
	s_addc_u32 s0, s65, 0
	v_writelane_b32 v254, s0, 12
	s_lshl_b32 s0, s10, 3
	s_add_i32 s60, s1, s0
	s_lshl_b32 s34, s11, 3
	s_cmp_lt_i32 s66, 1
	v_writelane_b32 v254, s1, 13
	s_cselect_b64 s[0:1], -1, 0
	s_cmp_gt_i32 s67, 0
	s_cselect_b64 s[2:3], -1, 0
	s_and_b64 s[0:1], s[0:1], s[2:3]
	s_andn2_b64 vcc, exec, s[0:1]
	v_and_b32_e32 v1, 63, v0
	s_cbranch_vccnz .LBB0_120
	s_waitcnt lgkmcnt(0)
	v_lshlrev_b32_e32 v2, 2, v0
	global_load_dword v100, v2, s[46:47]
	s_add_u32 s2, s46, 0x800
	s_addc_u32 s3, s47, 0
	global_load_dword v101, v2, s[2:3]
	s_add_u32 s2, s46, 0x1000
	s_addc_u32 s3, s47, 0
	global_load_dword v102, v2, s[2:3]
	s_add_u32 s2, s46, 0x1800
	s_addc_u32 s3, s47, 0
	global_load_dword v103, v2, s[2:3]
	s_add_u32 s2, s46, 0x2000
	s_addc_u32 s3, s47, 0
	global_load_dword v104, v2, s[2:3]
	s_add_u32 s2, s46, 0x2800
	s_addc_u32 s3, s47, 0
	global_load_dword v105, v2, s[2:3]
	s_add_u32 s2, s46, 0x3000
	s_addc_u32 s3, s47, 0
	global_load_dword v106, v2, s[2:3]
	s_add_u32 s2, s46, 0x3800
	s_addc_u32 s3, s47, 0
	global_load_dword v107, v2, s[2:3]
	global_load_dword v108, v2, s[44:45]
	s_add_u32 s2, s44, 0x800
	s_addc_u32 s3, s45, 0
	global_load_dword v109, v2, s[2:3]
	s_add_u32 s2, s44, 0x1000
	s_addc_u32 s3, s45, 0
	global_load_dword v110, v2, s[2:3]
	s_add_u32 s2, s44, 0x1800
	s_addc_u32 s3, s45, 0
	global_load_dword v111, v2, s[2:3]
	s_add_u32 s2, s44, 0x2000
	s_addc_u32 s3, s45, 0
	global_load_dword v112, v2, s[2:3]
	s_add_u32 s2, s44, 0x2800
	s_addc_u32 s3, s45, 0
	global_load_dword v113, v2, s[2:3]
	s_add_u32 s2, s44, 0x3000
	s_addc_u32 s3, s45, 0
	global_load_dword v114, v2, s[2:3]
	s_add_u32 s2, s44, 0x3800
	s_addc_u32 s3, s45, 0
	global_load_dword v115, v2, s[2:3]
	s_add_u32 s2, s44, 0x4000
	s_addc_u32 s3, s45, 0
	global_load_dword v116, v2, s[2:3]
	s_add_u32 s2, s44, 0x4800
	s_addc_u32 s3, s45, 0
	global_load_dword v117, v2, s[2:3]
	s_add_u32 s2, s44, 0x5000
	s_addc_u32 s3, s45, 0
	global_load_dword v118, v2, s[2:3]
	s_add_u32 s2, s44, 0x5800
	s_addc_u32 s3, s45, 0
	global_load_dword v119, v2, s[2:3]
	s_add_u32 s2, s44, 0x6000
	s_addc_u32 s3, s45, 0
	global_load_dword v120, v2, s[2:3]
	s_add_u32 s2, s44, 0x6800
	s_addc_u32 s3, s45, 0
	global_load_dword v121, v2, s[2:3]
	s_add_u32 s2, s44, 0x7000
	s_addc_u32 s3, s45, 0
	global_load_dword v122, v2, s[2:3]
	s_add_u32 s2, s44, 0x7800
	s_addc_u32 s3, s45, 0
	global_load_dword v123, v2, s[2:3]
	s_waitcnt vmcnt(0)
	v_mul_f32_e32 v10, 0xbfb8aa3b, v100
	v_exp_f32_e32 v10, v10
	s_nop 0
	v_add_f32_e32 v10, 1.0, v10
	v_div_scale_f32 v11, s[6:7], v10, v10, v100
	v_rcp_f32_e32 v12, v11
	v_div_scale_f32 v13, vcc, v100, v10, v100
	v_fma_f32 v14, -v11, v12, 1.0
	v_fmac_f32_e32 v12, v14, v12
	v_mul_f32_e32 v14, v13, v12
	v_fma_f32 v15, -v11, v14, v13
	v_fmac_f32_e32 v14, v15, v12
	v_fma_f32 v11, -v11, v14, v13
	v_div_fmas_f32 v11, v11, v12, v14
	v_div_fixup_f32 v2, v11, v10, v100
	ds_write_b32 v4, v2 offset:0
	v_mul_f32_e32 v10, 0xbfb8aa3b, v101
	v_exp_f32_e32 v10, v10
	s_nop 0
	v_add_f32_e32 v10, 1.0, v10
	v_div_scale_f32 v11, s[6:7], v10, v10, v101
	v_rcp_f32_e32 v12, v11
	v_div_scale_f32 v13, vcc, v101, v10, v101
	v_fma_f32 v14, -v11, v12, 1.0
	v_fmac_f32_e32 v12, v14, v12
	v_mul_f32_e32 v14, v13, v12
	v_fma_f32 v15, -v11, v14, v13
	v_fmac_f32_e32 v14, v15, v12
	v_fma_f32 v11, -v11, v14, v13
	v_div_fmas_f32 v11, v11, v12, v14
	v_div_fixup_f32 v2, v11, v10, v101
	ds_write_b32 v4, v2 offset:2048
	v_mul_f32_e32 v10, 0xbfb8aa3b, v102
	v_exp_f32_e32 v10, v10
	s_nop 0
	v_add_f32_e32 v10, 1.0, v10
	v_div_scale_f32 v11, s[6:7], v10, v10, v102
	v_rcp_f32_e32 v12, v11
	v_div_scale_f32 v13, vcc, v102, v10, v102
	v_fma_f32 v14, -v11, v12, 1.0
	v_fmac_f32_e32 v12, v14, v12
	v_mul_f32_e32 v14, v13, v12
	v_fma_f32 v15, -v11, v14, v13
	v_fmac_f32_e32 v14, v15, v12
	v_fma_f32 v11, -v11, v14, v13
	v_div_fmas_f32 v11, v11, v12, v14
	v_div_fixup_f32 v2, v11, v10, v102
	ds_write_b32 v4, v2 offset:4096
	v_mul_f32_e32 v10, 0xbfb8aa3b, v103
	v_exp_f32_e32 v10, v10
	s_nop 0
	v_add_f32_e32 v10, 1.0, v10
	v_div_scale_f32 v11, s[6:7], v10, v10, v103
	v_rcp_f32_e32 v12, v11
	v_div_scale_f32 v13, vcc, v103, v10, v103
	v_fma_f32 v14, -v11, v12, 1.0
	v_fmac_f32_e32 v12, v14, v12
	v_mul_f32_e32 v14, v13, v12
	v_fma_f32 v15, -v11, v14, v13
	v_fmac_f32_e32 v14, v15, v12
	v_fma_f32 v11, -v11, v14, v13
	v_div_fmas_f32 v11, v11, v12, v14
	v_div_fixup_f32 v2, v11, v10, v103
	ds_write_b32 v4, v2 offset:6144
	v_mul_f32_e32 v10, 0xbfb8aa3b, v104
	v_exp_f32_e32 v10, v10
	s_nop 0
	v_add_f32_e32 v10, 1.0, v10
	v_div_scale_f32 v11, s[6:7], v10, v10, v104
	v_rcp_f32_e32 v12, v11
	v_div_scale_f32 v13, vcc, v104, v10, v104
	v_fma_f32 v14, -v11, v12, 1.0
	v_fmac_f32_e32 v12, v14, v12
	v_mul_f32_e32 v14, v13, v12
	v_fma_f32 v15, -v11, v14, v13
	v_fmac_f32_e32 v14, v15, v12
	v_fma_f32 v11, -v11, v14, v13
	v_div_fmas_f32 v11, v11, v12, v14
	v_div_fixup_f32 v2, v11, v10, v104
	ds_write_b32 v4, v2 offset:8192
	v_mul_f32_e32 v10, 0xbfb8aa3b, v105
	v_exp_f32_e32 v10, v10
	s_nop 0
	v_add_f32_e32 v10, 1.0, v10
	v_div_scale_f32 v11, s[6:7], v10, v10, v105
	v_rcp_f32_e32 v12, v11
	v_div_scale_f32 v13, vcc, v105, v10, v105
	v_fma_f32 v14, -v11, v12, 1.0
	v_fmac_f32_e32 v12, v14, v12
	v_mul_f32_e32 v14, v13, v12
	v_fma_f32 v15, -v11, v14, v13
	v_fmac_f32_e32 v14, v15, v12
	v_fma_f32 v11, -v11, v14, v13
	v_div_fmas_f32 v11, v11, v12, v14
	v_div_fixup_f32 v2, v11, v10, v105
	ds_write_b32 v4, v2 offset:10240
	v_mul_f32_e32 v10, 0xbfb8aa3b, v106
	v_exp_f32_e32 v10, v10
	s_nop 0
	v_add_f32_e32 v10, 1.0, v10
	v_div_scale_f32 v11, s[6:7], v10, v10, v106
	v_rcp_f32_e32 v12, v11
	v_div_scale_f32 v13, vcc, v106, v10, v106
	v_fma_f32 v14, -v11, v12, 1.0
	v_fmac_f32_e32 v12, v14, v12
	v_mul_f32_e32 v14, v13, v12
	v_fma_f32 v15, -v11, v14, v13
	v_fmac_f32_e32 v14, v15, v12
	v_fma_f32 v11, -v11, v14, v13
	v_div_fmas_f32 v11, v11, v12, v14
	v_div_fixup_f32 v2, v11, v10, v106
	ds_write_b32 v4, v2 offset:12288
	v_mul_f32_e32 v10, 0xbfb8aa3b, v107
	v_exp_f32_e32 v10, v10
	s_nop 0
	v_add_f32_e32 v10, 1.0, v10
	v_div_scale_f32 v11, s[6:7], v10, v10, v107
	v_rcp_f32_e32 v12, v11
	v_div_scale_f32 v13, vcc, v107, v10, v107
	v_fma_f32 v14, -v11, v12, 1.0
	v_fmac_f32_e32 v12, v14, v12
	v_mul_f32_e32 v14, v13, v12
	v_fma_f32 v15, -v11, v14, v13
	v_fmac_f32_e32 v14, v15, v12
	v_fma_f32 v11, -v11, v14, v13
	v_div_fmas_f32 v11, v11, v12, v14
	v_div_fixup_f32 v2, v11, v10, v107
	ds_write_b32 v4, v2 offset:14336
	v_mul_f32_e32 v10, 0xbfb8aa3b, v108
	v_exp_f32_e32 v10, v10
	s_nop 0
	v_add_f32_e32 v10, 1.0, v10
	v_div_scale_f32 v11, s[6:7], v10, v10, v108
	v_rcp_f32_e32 v12, v11
	v_div_scale_f32 v13, vcc, v108, v10, v108
	v_fma_f32 v14, -v11, v12, 1.0
	v_fmac_f32_e32 v12, v14, v12
	v_mul_f32_e32 v14, v13, v12
	v_fma_f32 v15, -v11, v14, v13
	v_fmac_f32_e32 v14, v15, v12
	v_fma_f32 v11, -v11, v14, v13
	v_div_fmas_f32 v11, v11, v12, v14
	v_div_fixup_f32 v2, v11, v10, v108
	ds_write_b32 v4, v2 offset:16384
	v_mul_f32_e32 v10, 0xbfb8aa3b, v109
	v_exp_f32_e32 v10, v10
	s_nop 0
	v_add_f32_e32 v10, 1.0, v10
	v_div_scale_f32 v11, s[6:7], v10, v10, v109
	v_rcp_f32_e32 v12, v11
	v_div_scale_f32 v13, vcc, v109, v10, v109
	v_fma_f32 v14, -v11, v12, 1.0
	v_fmac_f32_e32 v12, v14, v12
	v_mul_f32_e32 v14, v13, v12
	v_fma_f32 v15, -v11, v14, v13
	v_fmac_f32_e32 v14, v15, v12
	v_fma_f32 v11, -v11, v14, v13
	v_div_fmas_f32 v11, v11, v12, v14
	v_div_fixup_f32 v2, v11, v10, v109
	ds_write_b32 v4, v2 offset:18432
	v_mul_f32_e32 v10, 0xbfb8aa3b, v110
	v_exp_f32_e32 v10, v10
	s_nop 0
	v_add_f32_e32 v10, 1.0, v10
	v_div_scale_f32 v11, s[6:7], v10, v10, v110
	v_rcp_f32_e32 v12, v11
	v_div_scale_f32 v13, vcc, v110, v10, v110
	v_fma_f32 v14, -v11, v12, 1.0
	v_fmac_f32_e32 v12, v14, v12
	v_mul_f32_e32 v14, v13, v12
	v_fma_f32 v15, -v11, v14, v13
	v_fmac_f32_e32 v14, v15, v12
	v_fma_f32 v11, -v11, v14, v13
	v_div_fmas_f32 v11, v11, v12, v14
	v_div_fixup_f32 v2, v11, v10, v110
	ds_write_b32 v4, v2 offset:20480
	v_mul_f32_e32 v10, 0xbfb8aa3b, v111
	v_exp_f32_e32 v10, v10
	s_nop 0
	v_add_f32_e32 v10, 1.0, v10
	v_div_scale_f32 v11, s[6:7], v10, v10, v111
	v_rcp_f32_e32 v12, v11
	v_div_scale_f32 v13, vcc, v111, v10, v111
	v_fma_f32 v14, -v11, v12, 1.0
	v_fmac_f32_e32 v12, v14, v12
	v_mul_f32_e32 v14, v13, v12
	v_fma_f32 v15, -v11, v14, v13
	v_fmac_f32_e32 v14, v15, v12
	v_fma_f32 v11, -v11, v14, v13
	v_div_fmas_f32 v11, v11, v12, v14
	v_div_fixup_f32 v2, v11, v10, v111
	ds_write_b32 v4, v2 offset:22528
	v_mul_f32_e32 v10, 0xbfb8aa3b, v112
	v_exp_f32_e32 v10, v10
	s_nop 0
	v_add_f32_e32 v10, 1.0, v10
	v_div_scale_f32 v11, s[6:7], v10, v10, v112
	v_rcp_f32_e32 v12, v11
	v_div_scale_f32 v13, vcc, v112, v10, v112
	v_fma_f32 v14, -v11, v12, 1.0
	v_fmac_f32_e32 v12, v14, v12
	v_mul_f32_e32 v14, v13, v12
	v_fma_f32 v15, -v11, v14, v13
	v_fmac_f32_e32 v14, v15, v12
	v_fma_f32 v11, -v11, v14, v13
	v_div_fmas_f32 v11, v11, v12, v14
	v_div_fixup_f32 v2, v11, v10, v112
	ds_write_b32 v4, v2 offset:24576
	v_mul_f32_e32 v10, 0xbfb8aa3b, v113
	v_exp_f32_e32 v10, v10
	s_nop 0
	v_add_f32_e32 v10, 1.0, v10
	v_div_scale_f32 v11, s[6:7], v10, v10, v113
	v_rcp_f32_e32 v12, v11
	v_div_scale_f32 v13, vcc, v113, v10, v113
	v_fma_f32 v14, -v11, v12, 1.0
	v_fmac_f32_e32 v12, v14, v12
	v_mul_f32_e32 v14, v13, v12
	v_fma_f32 v15, -v11, v14, v13
	v_fmac_f32_e32 v14, v15, v12
	v_fma_f32 v11, -v11, v14, v13
	v_div_fmas_f32 v11, v11, v12, v14
	v_div_fixup_f32 v2, v11, v10, v113
	ds_write_b32 v4, v2 offset:26624
	v_mul_f32_e32 v10, 0xbfb8aa3b, v114
	v_exp_f32_e32 v10, v10
	s_nop 0
	v_add_f32_e32 v10, 1.0, v10
	v_div_scale_f32 v11, s[6:7], v10, v10, v114
	v_rcp_f32_e32 v12, v11
	v_div_scale_f32 v13, vcc, v114, v10, v114
	v_fma_f32 v14, -v11, v12, 1.0
	v_fmac_f32_e32 v12, v14, v12
	v_mul_f32_e32 v14, v13, v12
	v_fma_f32 v15, -v11, v14, v13
	v_fmac_f32_e32 v14, v15, v12
	v_fma_f32 v11, -v11, v14, v13
	v_div_fmas_f32 v11, v11, v12, v14
	v_div_fixup_f32 v2, v11, v10, v114
	ds_write_b32 v4, v2 offset:28672
	v_mul_f32_e32 v10, 0xbfb8aa3b, v115
	v_exp_f32_e32 v10, v10
	s_nop 0
	v_add_f32_e32 v10, 1.0, v10
	v_div_scale_f32 v11, s[6:7], v10, v10, v115
	v_rcp_f32_e32 v12, v11
	v_div_scale_f32 v13, vcc, v115, v10, v115
	v_fma_f32 v14, -v11, v12, 1.0
	v_fmac_f32_e32 v12, v14, v12
	v_mul_f32_e32 v14, v13, v12
	v_fma_f32 v15, -v11, v14, v13
	v_fmac_f32_e32 v14, v15, v12
	v_fma_f32 v11, -v11, v14, v13
	v_div_fmas_f32 v11, v11, v12, v14
	v_div_fixup_f32 v2, v11, v10, v115
	ds_write_b32 v4, v2 offset:30720
	v_mul_f32_e32 v10, 0xbfb8aa3b, v116
	v_exp_f32_e32 v10, v10
	s_nop 0
	v_add_f32_e32 v10, 1.0, v10
	v_div_scale_f32 v11, s[6:7], v10, v10, v116
	v_rcp_f32_e32 v12, v11
	v_div_scale_f32 v13, vcc, v116, v10, v116
	v_fma_f32 v14, -v11, v12, 1.0
	v_fmac_f32_e32 v12, v14, v12
	v_mul_f32_e32 v14, v13, v12
	v_fma_f32 v15, -v11, v14, v13
	v_fmac_f32_e32 v14, v15, v12
	v_fma_f32 v11, -v11, v14, v13
	v_div_fmas_f32 v11, v11, v12, v14
	v_div_fixup_f32 v2, v11, v10, v116
	ds_write_b32 v4, v2 offset:32768
	v_mul_f32_e32 v10, 0xbfb8aa3b, v117
	v_exp_f32_e32 v10, v10
	s_nop 0
	v_add_f32_e32 v10, 1.0, v10
	v_div_scale_f32 v11, s[6:7], v10, v10, v117
	v_rcp_f32_e32 v12, v11
	v_div_scale_f32 v13, vcc, v117, v10, v117
	v_fma_f32 v14, -v11, v12, 1.0
	v_fmac_f32_e32 v12, v14, v12
	v_mul_f32_e32 v14, v13, v12
	v_fma_f32 v15, -v11, v14, v13
	v_fmac_f32_e32 v14, v15, v12
	v_fma_f32 v11, -v11, v14, v13
	v_div_fmas_f32 v11, v11, v12, v14
	v_div_fixup_f32 v2, v11, v10, v117
	ds_write_b32 v4, v2 offset:34816
	v_mul_f32_e32 v10, 0xbfb8aa3b, v118
	v_exp_f32_e32 v10, v10
	s_nop 0
	v_add_f32_e32 v10, 1.0, v10
	v_div_scale_f32 v11, s[6:7], v10, v10, v118
	v_rcp_f32_e32 v12, v11
	v_div_scale_f32 v13, vcc, v118, v10, v118
	v_fma_f32 v14, -v11, v12, 1.0
	v_fmac_f32_e32 v12, v14, v12
	v_mul_f32_e32 v14, v13, v12
	v_fma_f32 v15, -v11, v14, v13
	v_fmac_f32_e32 v14, v15, v12
	v_fma_f32 v11, -v11, v14, v13
	v_div_fmas_f32 v11, v11, v12, v14
	v_div_fixup_f32 v2, v11, v10, v118
	ds_write_b32 v4, v2 offset:36864
	v_mul_f32_e32 v10, 0xbfb8aa3b, v119
	v_exp_f32_e32 v10, v10
	s_nop 0
	v_add_f32_e32 v10, 1.0, v10
	v_div_scale_f32 v11, s[6:7], v10, v10, v119
	v_rcp_f32_e32 v12, v11
	v_div_scale_f32 v13, vcc, v119, v10, v119
	v_fma_f32 v14, -v11, v12, 1.0
	v_fmac_f32_e32 v12, v14, v12
	v_mul_f32_e32 v14, v13, v12
	v_fma_f32 v15, -v11, v14, v13
	v_fmac_f32_e32 v14, v15, v12
	v_fma_f32 v11, -v11, v14, v13
	v_div_fmas_f32 v11, v11, v12, v14
	v_div_fixup_f32 v2, v11, v10, v119
	ds_write_b32 v4, v2 offset:38912
	v_mul_f32_e32 v10, 0xbfb8aa3b, v120
	v_exp_f32_e32 v10, v10
	s_nop 0
	v_add_f32_e32 v10, 1.0, v10
	v_div_scale_f32 v11, s[6:7], v10, v10, v120
	v_rcp_f32_e32 v12, v11
	v_div_scale_f32 v13, vcc, v120, v10, v120
	v_fma_f32 v14, -v11, v12, 1.0
	v_fmac_f32_e32 v12, v14, v12
	v_mul_f32_e32 v14, v13, v12
	v_fma_f32 v15, -v11, v14, v13
	v_fmac_f32_e32 v14, v15, v12
	v_fma_f32 v11, -v11, v14, v13
	v_div_fmas_f32 v11, v11, v12, v14
	v_div_fixup_f32 v2, v11, v10, v120
	ds_write_b32 v4, v2 offset:40960
	v_mul_f32_e32 v10, 0xbfb8aa3b, v121
	v_exp_f32_e32 v10, v10
	s_nop 0
	v_add_f32_e32 v10, 1.0, v10
	v_div_scale_f32 v11, s[6:7], v10, v10, v121
	v_rcp_f32_e32 v12, v11
	v_div_scale_f32 v13, vcc, v121, v10, v121
	v_fma_f32 v14, -v11, v12, 1.0
	v_fmac_f32_e32 v12, v14, v12
	v_mul_f32_e32 v14, v13, v12
	v_fma_f32 v15, -v11, v14, v13
	v_fmac_f32_e32 v14, v15, v12
	v_fma_f32 v11, -v11, v14, v13
	v_div_fmas_f32 v11, v11, v12, v14
	v_div_fixup_f32 v2, v11, v10, v121
	ds_write_b32 v4, v2 offset:43008
	v_mul_f32_e32 v10, 0xbfb8aa3b, v122
	v_exp_f32_e32 v10, v10
	s_nop 0
	v_add_f32_e32 v10, 1.0, v10
	v_div_scale_f32 v11, s[6:7], v10, v10, v122
	v_rcp_f32_e32 v12, v11
	v_div_scale_f32 v13, vcc, v122, v10, v122
	v_fma_f32 v14, -v11, v12, 1.0
	v_fmac_f32_e32 v12, v14, v12
	v_mul_f32_e32 v14, v13, v12
	v_fma_f32 v15, -v11, v14, v13
	v_fmac_f32_e32 v14, v15, v12
	v_fma_f32 v11, -v11, v14, v13
	v_div_fmas_f32 v11, v11, v12, v14
	v_div_fixup_f32 v2, v11, v10, v122
	ds_write_b32 v4, v2 offset:45056
	v_mul_f32_e32 v10, 0xbfb8aa3b, v123
	v_exp_f32_e32 v10, v10
	s_nop 0
	v_add_f32_e32 v10, 1.0, v10
	v_div_scale_f32 v11, s[6:7], v10, v10, v123
	v_rcp_f32_e32 v12, v11
	v_div_scale_f32 v13, vcc, v123, v10, v123
	v_fma_f32 v14, -v11, v12, 1.0
	v_fmac_f32_e32 v12, v14, v12
	v_mul_f32_e32 v14, v13, v12
	v_fma_f32 v15, -v11, v14, v13
	v_fmac_f32_e32 v14, v15, v12
	v_fma_f32 v11, -v11, v14, v13
	v_div_fmas_f32 v11, v11, v12, v14
	v_div_fixup_f32 v2, v11, v10, v123
	ds_write_b32 v4, v2 offset:47104
	s_mov_b64 s[0:1], -1
	s_or_b64 exec, exec, s[0:1]
	v_readlane_b32 s1, v254, 13
	s_mul_i32 s0, s1, 0xc00
	s_add_i32 s35, s0, 0
	s_lshl_b32 s33, s1, 5
	s_cmpk_gt_i32 s10, 0x8ff
	s_waitcnt lgkmcnt(0)
	s_barrier
	s_cbranch_scc1 .LBB0_24
	v_mov_b32_e32 v3, 2
	v_lshlrev_b32_sdwa v14, v3, v0 dst_sel:DWORD dst_unused:UNUSED_PAD src0_sel:DWORD src1_sel:BYTE_0
	v_lshrrev_b32_e32 v26, 8, v0
	v_lshl_or_b32 v3, v26, 10, v14
	v_lshlrev_b32_e32 v2, 2, v1
	v_mov_b32_e32 v15, 0
	s_movk_i32 s0, 0x300
	v_add_u32_e32 v3, 0, v3
	v_cmp_gt_u32_e64 s[2:3], s0, v0
	v_lshl_add_u32 v24, v1, 4, s35
	s_movk_i32 s8, 0xff
	v_lshl_add_u64 v[16:17], s[92:93], 0, v[14:15]
	v_or_b32_e32 v25, 0xfffffe00, v0
	v_add_u32_e32 v27, 0xc000, v3
	s_mov_b32 s44, 0x24000
	v_lshlrev_b32_e32 v18, 2, v2
	v_mov_b32_e32 v19, v15
	s_mov_b32 s45, 0x48000
	s_mov_b32 s46, 0x6c000
	s_mov_b32 s47, 0x90000
	s_mov_b32 s61, 0xb4000
	s_mov_b32 s68, 0xd8000
	s_mov_b32 s69, 0xfc000
	s_mov_b32 s70, 0x120000
	s_mov_b32 s71, 0x144000
	s_mov_b32 s72, 0x168000
	s_mov_b32 s9, 0x18c000
	s_mov_b32 s73, 0x1b0000
	s_mov_b32 s74, 0x1d4000
	s_mov_b32 s75, 0x1f8000
	s_mov_b32 s76, 0x21c000
	s_mov_b32 s77, s10
	s_branch .LBB0_17
